# P0: weight-transpose items rotated by 1024 waves so the 128 waves with two items are not the ones that also norm a sample row (on top of hand-written decode)
# speedup vs baseline: 1.0012x; 1.0012x over previous
.LBB0_48:
	v_writelane_b32 v252, s24, 48
	s_load_dwordx16 s[40:55], s[0:1], 0x0
	s_load_dword s2, s[0:1], 0xf8
	v_writelane_b32 v252, s25, 49
	v_writelane_b32 v252, s26, 50
	v_writelane_b32 v252, s27, 51
	v_writelane_b32 v252, s28, 52
	v_writelane_b32 v252, s29, 53
	v_writelane_b32 v252, s30, 54
	v_writelane_b32 v252, s31, 55
	s_waitcnt lgkmcnt(0)
	s_lshl_b32 s38, s2, 3
	s_lshl_b32 s2, s83, 3
	v_readlane_b32 s3, v252, 47
	s_add_i32 s62, s2, s3
	s_cmpk_gt_i32 s62, 0x87f
	s_cbranch_scc1 .LBB0_59
	s_add_i32 s99, s62, 0x400
	s_and_b32 s99, s99, 0x7ff
	s_cmpk_eq_i32 s38, 0x800
	s_cselect_b32 s99, s99, s62
	v_readlane_b32 s2, v252, 47
	s_lshl_b32 s2, s2, 14
	v_lshrrev_b32_e32 v1, 5, v228
	v_and_b32_e32 v2, 31, v0
	s_load_dwordx8 s[16:23], s[0:1], 0xc0
	s_add_i32 s4, s2, 0
	v_lshlrev_b32_e32 v2, 2, v2
	v_mul_u32_u24_e32 v6, 0x84, v1
	v_add3_u32 v16, s4, v2, v6
	v_lshlrev_b32_e32 v6, 3, v0
	v_lshrrev_b32_e32 v17, 3, v228
	v_and_b32_e32 v6, 56, v6
	v_mov_b32_e32 v3, 0
	v_mul_u32_u24_e32 v8, 0x84, v6
	v_lshlrev_b32_e32 v9, 2, v17
	s_waitcnt lgkmcnt(0)
	v_lshl_add_u64 v[4:5], s[18:19], 0, v[2:3]
	v_add3_u32 v18, s4, v8, v9
	v_lshl_add_u64 v[8:9], s[22:23], 0, v[2:3]
	s_load_dwordx16 s[16:31], s[0:1], 0x40
	v_lshlrev_b32_e32 v6, 1, v6
	v_mov_b32_e32 v7, v3
	v_lshl_add_u64 v[14:15], s[12:13], 0, v[6:7]
	s_mov_b64 s[2:3], 0xa00000
	v_lshl_add_u64 v[6:7], v[14:15], 0, s[2:3]
	s_mov_b64 s[2:3], 0x800000
	v_lshl_add_u64 v[10:11], v[14:15], 0, s[2:3]
	s_mov_b64 s[2:3], 0x200000
	s_lshl_b32 s4, s99, 1
	s_mov_b32 s7, 0
	v_or_b32_e32 v19, 8, v17
	v_or_b32_e32 v20, 16, v17
	v_or_b32_e32 v21, 24, v17
	s_waitcnt lgkmcnt(0)
	v_lshl_add_u64 v[12:13], s[16:17], 0, v[2:3]
	v_lshl_add_u64 v[14:15], v[14:15], 0, s[2:3]
	s_lshl_b32 s2, s99, 5
	s_lshl_b32 s3, s38, 5
	s_lshl_b32 s10, s99, 7
	s_lshl_b32 s11, s38, 7
	s_lshl_b32 s14, s99, 2
	s_lshl_b32 s15, s38, 2
	s_add_i32 s16, s4, 0x1f400
	s_lshl_b32 s17, s38, 1
	s_movk_i32 s18, 0x3000
	s_movk_i32 s19, 0x7fff
	s_mov_b32 s20, 0xffff0000
	v_add_u32_e32 v22, 0x400, v16
	v_add_u32_e32 v23, 0x800, v16
	v_add_u32_e32 v24, 0xc00, v16
	v_add_u32_e32 v25, 0x1000, v16
	v_add_u32_e32 v26, 0x1400, v16
	v_add_u32_e32 v27, 0x1800, v16
	v_add_u32_e32 v28, 0x1c00, v16
	s_mov_b32 s21, s99
	s_branch .LBB0_51

	.amdhsa_kernel _Z9hymba_fwd4Args
		.amdhsa_group_segment_fixed_size 0
		.amdhsa_private_segment_fixed_size 0
		.amdhsa_kernarg_size 504
		.amdhsa_user_sgpr_count 2
		.amdhsa_user_sgpr_dispatch_ptr 0
		.amdhsa_user_sgpr_queue_ptr 0
		.amdhsa_user_sgpr_kernarg_segment_ptr 1
		.amdhsa_user_sgpr_dispatch_id 0
		.amdhsa_user_sgpr_kernarg_preload_length 0
		.amdhsa_user_sgpr_kernarg_preload_offset 0
		.amdhsa_user_sgpr_private_segment_size 0
		.amdhsa_uses_dynamic_stack 0
		.amdhsa_enable_private_segment 0
		.amdhsa_system_sgpr_workgroup_id_x 1
		.amdhsa_system_sgpr_workgroup_id_y 0
		.amdhsa_system_sgpr_workgroup_id_z 0
		.amdhsa_system_sgpr_workgroup_info 0
		.amdhsa_system_vgpr_workitem_id 0
		.amdhsa_next_free_vgpr 253
		.amdhsa_next_free_sgpr 102
		.amdhsa_accum_offset 256
		.amdhsa_reserve_vcc 1
		.amdhsa_float_round_mode_32 0
		.amdhsa_float_round_mode_16_64 0
		.amdhsa_float_denorm_mode_32 3
		.amdhsa_float_denorm_mode_16_64 3
		.amdhsa_dx10_clamp 1
		.amdhsa_ieee_mode 1
		.amdhsa_fp16_overflow 0
		.amdhsa_tg_split 0
		.amdhsa_exception_fp_ieee_invalid_op 0
		.amdhsa_exception_fp_denorm_src 0
		.amdhsa_exception_fp_ieee_div_zero 0
		.amdhsa_exception_fp_ieee_overflow 0
		.amdhsa_exception_fp_ieee_underflow 0
		.amdhsa_exception_fp_ieee_inexact 0
		.amdhsa_exception_int_div_zero 0
	.end_amdhsa_kernel

amdhsa.kernels:
  - .agpr_count:     0
    .args:
      - .offset:         0
        .size:           248
        .value_kind:     by_value
      - .offset:         248
        .size:           4
        .value_kind:     hidden_block_count_x
      - .offset:         252
        .size:           4
        .value_kind:     hidden_block_count_y
      - .offset:         256
        .size:           4
        .value_kind:     hidden_block_count_z
      - .offset:         260
        .size:           2
        .value_kind:     hidden_group_size_x
      - .offset:         262
        .size:           2
        .value_kind:     hidden_group_size_y
      - .offset:         264
        .size:           2
        .value_kind:     hidden_group_size_z
      - .offset:         266
        .size:           2
        .value_kind:     hidden_remainder_x
      - .offset:         268
        .size:           2
        .value_kind:     hidden_remainder_y
      - .offset:         270
        .size:           2
        .value_kind:     hidden_remainder_z
      - .offset:         288
        .size:           8
        .value_kind:     hidden_global_offset_x
      - .offset:         296
        .size:           8
        .value_kind:     hidden_global_offset_y
      - .offset:         304
        .size:           8
        .value_kind:     hidden_global_offset_z
      - .offset:         312
        .size:           2
        .value_kind:     hidden_grid_dims
      - .offset:         368
        .size:           4
        .value_kind:     hidden_dynamic_lds_size
    .group_segment_fixed_size: 0
    .kernarg_segment_align: 8
    .kernarg_segment_size: 504
    .language:       OpenCL C
    .language_version:
      - 2
      - 0
    .max_flat_workgroup_size: 512
    .name:           _Z9hymba_fwd4Args
    .private_segment_fixed_size: 0
    .sgpr_count:     108
    .sgpr_spill_count: 82
    .symbol:         _Z9hymba_fwd4Args.kd
    .uniform_work_group_size: 1
    .uses_dynamic_stack: false
    .vgpr_count:     253
    .vgpr_spill_count: 0
    .wavefront_size: 64
